# prologue de-serialisation: FFN2-up rstd table built for two units at a time (waves 4-7 take the odd units)
# baseline (speedup 1.0000x reference)
.LBB0_1653:
	s_cmp_lt_i32 s68, 9
	s_cselect_b64 s[0:1], -1, 0
	s_and_b64 s[6:7], s[0:1], s[2:3]
	s_andn2_b64 vcc, exec, s[6:7]
	s_cbranch_vccnz .LBB0_1710
	v_lshlrev_b32_e32 v8, 2, v199
	s_ashr_i32 s39, s38, 31
	s_movk_i32 s0, 0x100
	v_and_b32_e32 v232, 0xff, v199
	v_lshlrev_b32_e32 v0, 2, v232
	s_ashr_i32 s44, s34, 31
	s_mov_b32 s45, s34
	s_mov_b64 s[2:3], exec
	v_add_u32_e32 v2, 0x20200, v0
	s_movk_i32 s10, 0xc400
	s_waitcnt lgkmcnt(0)
	v_mov_b64_e32 v[0:1], 0x57f
	s_movk_i32 s11, 0xb1
	v_mov_b32_e32 v3, 0x358637bd
	s_mov_b32 s12, 0xf800000
	v_mov_b32_e32 v4, 0x260
	s_mov_b64 s[4:5], s[38:39]
	v_readfirstlane_b32 s13, v199
	s_nop 3
	s_cmp_lt_u32 s13, 0x100
	s_cbranch_scc1 .Lrt8_w0
	s_addk_i32 s10, 0x400
	s_add_u32 s4, s4, s45
	s_addc_u32 s5, s5, s44
.Lrt8_w0:
	s_branch .LBB0_1657
.LBB0_1655:
	s_or_b64 exec, exec, s[8:9]
	s_addk_i32 s10, 0x800
	s_add_u32 s4, s4, s45
	s_addc_u32 s5, s5, s44
	s_add_u32 s4, s4, s45
	s_addc_u32 s5, s5, s44
	s_cmp_ge_i32 s10, 0
	s_cselect_b64 s[0:1], -1, 0

.LBB0_1657:
	v_cmp_gt_i64_e32 vcc, s[4:5], v[0:1]
	s_mov_b64 s[0:1], -1
	s_cbranch_vccnz .LBB0_1656
	s_and_saveexec_b64 s[8:9], s[2:3]
	s_cbranch_execz .LBB0_1655
	s_ashr_i32 s0, s4, 31
	s_lshr_b32 s0, s0, 29
	s_add_i32 s0, s4, s0
	s_ashr_i32 s1, s0, 3
	s_and_b32 s0, s0, -8
	s_sub_i32 s0, s4, s0
	s_cmp_lt_i32 s0, 0
	s_cselect_b32 s13, s11, 0xb0
	s_mul_i32 s0, s0, s13
	s_add_i32 s0, s0, s1
	s_mul_hi_i32 s1, s0, 0x2e8ba2e9
	s_lshr_b32 s13, s1, 31
	s_ashr_i32 s1, s1, 4
	s_add_i32 s1, s1, s13
	s_lshl_b32 s13, s1, 2
	s_sub_i32 s14, 64, s13
	s_min_i32 s14, s14, 4
	s_abs_i32 s14, s14
	v_cvt_f32_u32_e32 v5, s14
	s_sub_i32 s15, 0, s14
	s_mulk_i32 s1, 0x58
	s_sub_i32 s0, s0, s1
	v_rcp_iflag_f32_e32 v5, v5
	s_ashr_i32 s1, s0, 31
	s_abs_i32 s0, s0
	v_mul_f32_e32 v5, 0x4f7ffffe, v5
	v_cvt_u32_f32_e32 v5, v5
	s_nop 0
	v_readfirstlane_b32 s16, v5
	s_mul_i32 s15, s15, s16
	s_mul_hi_u32 s15, s16, s15
	s_add_i32 s16, s16, s15
	s_mul_hi_u32 s15, s0, s16
	s_mul_i32 s15, s15, s14
	s_sub_i32 s0, s0, s15
	s_sub_i32 s15, s0, s14
	s_cmp_ge_u32 s0, s14
	s_cselect_b32 s0, s15, s0
	s_sub_i32 s15, s0, s14
	s_cmp_ge_u32 s0, s14
	s_cselect_b32 s0, s15, s0
	s_xor_b32 s0, s0, s1
	s_sub_i32 s0, s0, s1
	s_add_i32 s0, s0, s13
	v_lshl_or_b32 v6, s0, 8, v232
	v_ashrrev_i32_e32 v7, 31, v6
	v_lshlrev_b64 v[6:7], 6, v[6:7]
	v_lshl_add_u64 v[6:7], s[60:61], 0, v[6:7]
	global_load_dwordx4 v[10:13], v[6:7], off
	global_load_dwordx4 v[14:17], v[6:7], off offset:16
	global_load_dwordx4 v[18:21], v[6:7], off offset:32
	global_load_dwordx4 v[22:25], v[6:7], off offset:48
	s_waitcnt vmcnt(0)
	v_pk_add_f32 v[6:7], v[12:13], v[16:17]
	v_pk_add_f32 v[10:11], v[10:11], v[14:15]
	v_pk_add_f32 v[12:13], v[20:21], v[24:25]
	v_pk_add_f32 v[14:15], v[18:19], v[22:23]
	v_pk_add_f32 v[6:7], v[6:7], v[12:13]
	v_pk_add_f32 v[10:11], v[10:11], v[14:15]
	s_nop 0
	v_pk_mov_b32 v[12:13], v[10:11], v[6:7] op_sel:[1,0]
	v_mov_b32_e32 v11, v7
	v_pk_add_f32 v[6:7], v[12:13], v[10:11]
	s_nop 0
	v_add_f32_e32 v5, v6, v7
	v_fmamk_f32 v5, v5, 0x3a800000, v3
	v_mul_f32_e32 v6, 0x4f800000, v5
	v_cmp_gt_f32_e32 vcc, s12, v5
	s_nop 1
	v_cndmask_b32_e32 v5, v5, v6, vcc
	v_sqrt_f32_e32 v6, v5
	s_nop 0
	v_add_u32_e32 v7, -1, v6
	v_add_u32_e32 v9, 1, v6
	v_fma_f32 v10, -v7, v6, v5
	v_fma_f32 v11, -v9, v6, v5
	v_cmp_ge_f32_e64 s[0:1], 0, v10
	s_nop 1
	v_cndmask_b32_e64 v6, v6, v7, s[0:1]
	v_cmp_lt_f32_e64 s[0:1], 0, v11
	s_nop 1
	v_cndmask_b32_e64 v6, v6, v9, s[0:1]
	v_mul_f32_e32 v7, 0x37800000, v6
	v_cndmask_b32_e32 v6, v6, v7, vcc
	v_cmp_class_f32_e32 vcc, v5, v4
	s_nop 1
	v_cndmask_b32_e32 v5, v6, v5, vcc
	v_div_scale_f32 v6, s[0:1], v5, v5, 1.0
	v_rcp_f32_e32 v7, v6
	v_div_scale_f32 v9, vcc, 1.0, v5, 1.0
	v_fma_f32 v10, -v6, v7, 1.0
	v_fmac_f32_e32 v7, v10, v7
	v_mul_f32_e32 v10, v9, v7
	v_fma_f32 v11, -v6, v10, v9
	v_fmac_f32_e32 v10, v11, v7
	v_fma_f32 v6, -v6, v10, v9
	v_div_fmas_f32 v6, v6, v7, v10
	v_div_fixup_f32 v5, v6, v5, 1.0
	v_add_u32_e32 v6, s10, v2
	ds_write_b32 v6, v5 offset:15360
	s_branch .LBB0_1655
